# GLA/SSD pass-B operand staging: 8 loads in flight + one wait instead of 4 serialized load->wait->ds_write round trips
# speedup vs baseline: 1.1322x; 1.0125x over previous
.Lqk_10107_0:
	s_or_b64 exec, exec, s[40:41]
	v_cmp_gt_i32_e32 vcc, s76, v153
	v_mov_b32_e32 v36, 0
	v_mov_b32_e32 v37, 0
	v_mov_b32_e32 v38, 0
	v_mov_b32_e32 v39, 0
	v_mov_b32_e32 v40, 0
	v_mov_b32_e32 v41, 0
	v_mov_b32_e32 v42, 0
	v_mov_b32_e32 v43, 0
	s_and_saveexec_b64 s[40:41], vcc
	s_cbranch_execz .Lqk_10107_1
	v_add_u32_e32 v2, s73, v153
	v_ashrrev_i32_e32 v3, 31, v2
	v_lshlrev_b64 v[2:3], 10, v[2:3]
	v_lshl_or_b32 v2, v172, 1, v2
	v_lshl_add_u64 v[40:41], s[96:97], 0, v[2:3]
	v_lshl_add_u64 v[2:3], s[94:95], 0, v[2:3]
	global_load_dwordx4 v[36:39], v[2:3], off
	s_nop 0
	global_load_dwordx4 v[40:43], v[40:41], off
.Lqk_10107_1:
	s_or_b64 exec, exec, s[40:41]
	v_cmp_gt_i32_e32 vcc, s76, v155
	v_mov_b32_e32 v44, 0
	v_mov_b32_e32 v45, 0
	v_mov_b32_e32 v46, 0
	v_mov_b32_e32 v47, 0
	v_mov_b32_e32 v48, 0
	v_mov_b32_e32 v49, 0
	v_mov_b32_e32 v50, 0
	v_mov_b32_e32 v51, 0
	s_and_saveexec_b64 s[40:41], vcc
	s_cbranch_execz .Lqk_10107_2
	v_add_u32_e32 v2, s73, v155
	v_ashrrev_i32_e32 v3, 31, v2
	v_lshlrev_b64 v[2:3], 10, v[2:3]
	v_lshl_or_b32 v2, v172, 1, v2
	v_lshl_add_u64 v[48:49], s[96:97], 0, v[2:3]
	v_lshl_add_u64 v[2:3], s[94:95], 0, v[2:3]
	global_load_dwordx4 v[44:47], v[2:3], off
	s_nop 0
	global_load_dwordx4 v[48:51], v[48:49], off
.Lqk_10107_2:
	s_or_b64 exec, exec, s[40:41]
	v_cmp_gt_i32_e32 vcc, s76, v157
	v_mov_b32_e32 v52, 0
	v_mov_b32_e32 v53, 0
	v_mov_b32_e32 v54, 0
	v_mov_b32_e32 v55, 0
	v_mov_b32_e32 v64, 0
	v_mov_b32_e32 v65, 0
	v_mov_b32_e32 v66, 0
	v_mov_b32_e32 v67, 0
	s_and_saveexec_b64 s[40:41], vcc
	s_cbranch_execz .Lqk_10107_3
	v_add_u32_e32 v2, s73, v157
	v_ashrrev_i32_e32 v3, 31, v2
	v_lshlrev_b64 v[2:3], 10, v[2:3]
	v_lshl_or_b32 v2, v172, 1, v2
	v_lshl_add_u64 v[64:65], s[96:97], 0, v[2:3]
	v_lshl_add_u64 v[2:3], s[94:95], 0, v[2:3]
	global_load_dwordx4 v[52:55], v[2:3], off
	s_nop 0
	global_load_dwordx4 v[64:67], v[64:65], off
.Lqk_10107_3:
	s_or_b64 exec, exec, s[40:41]
	s_waitcnt vmcnt(0)
	ds_write_b128 v152, v[74:77] offset:27648
	ds_write_b128 v152, v[70:73] offset:45056
	ds_write_b128 v154, v[36:39] offset:27648
	ds_write_b128 v154, v[40:43] offset:45056
	ds_write_b128 v156, v[44:47] offset:27648
	ds_write_b128 v156, v[48:51] offset:45056
	ds_write_b128 v158, v[52:55] offset:27648
	ds_write_b128 v158, v[64:67] offset:45056
	s_add_i32 s72, s72, 1
	s_cmp_ge_u32 s72, s50
	v_mov_b64_e32 v[70:71], v[62:63]
	v_mov_b64_e32 v[68:69], v[60:61]
	v_mov_b64_e32 v[74:75], v[58:59]
	v_mov_b64_e32 v[72:73], v[56:57]
	s_waitcnt lgkmcnt(0)
	s_barrier
	s_cbranch_scc1 .LBB0_684
	s_add_i32 s40, s42, 1
	s_cmpk_lt_i32 s42, 0xff
	s_cselect_b64 s[42:43], -1, 0
	s_ashr_i32 s41, s40, 31
	v_mov_b32_e32 v40, v0
	v_mov_b32_e32 v41, v0
	s_lshl_b64 s[44:45], s[40:41], 9
	v_mov_b32_e32 v42, v0
	v_mov_b32_e32 v43, v0
	v_mov_b64_e32 v[36:37], v[40:41]
	s_or_b64 s[42:43], s[42:43], s[4:5]
	s_or_b64 s[44:45], s[44:45], s[52:53]
	v_mov_b64_e32 v[38:39], v[42:43]
	s_and_saveexec_b64 s[48:49], s[42:43]
	s_cbranch_execz .LBB0_673
	v_lshl_add_u64 v[2:3], s[44:45], 0, v[144:145]
	v_lshlrev_b64 v[2:3], 7, v[2:3]
	v_lshl_add_u64 v[2:3], v[130:131], 0, v[2:3]
	global_load_dwordx4 v[36:39], v[2:3], off

.Lcb_31495_0:
	s_or_b64 exec, exec, s[54:55]
	v_cmp_gt_i32_e32 vcc, s76, v121
	v_mov_b32_e32 v36, 0
	v_mov_b32_e32 v37, 0
	v_mov_b32_e32 v38, 0
	v_mov_b32_e32 v39, 0
	v_mov_b32_e32 v40, 0
	v_mov_b32_e32 v41, 0
	v_mov_b32_e32 v42, 0
	v_mov_b32_e32 v43, 0
	s_and_saveexec_b64 s[54:55], vcc
	s_cbranch_execz .Lcb_31495_1
	v_add_u32_e32 v2, s77, v121
	v_ashrrev_i32_e32 v3, 31, v2
	v_lshlrev_b64 v[2:3], 10, v[2:3]
	v_lshl_or_b32 v2, v150, 1, v2
	v_lshl_add_u64 v[40:41], s[80:81], 0, v[2:3]
	v_lshl_add_u64 v[2:3], s[88:89], 0, v[2:3]
	global_load_dwordx4 v[36:39], v[40:41], off
	s_nop 0
	global_load_dwordx4 v[40:43], v[2:3], off
.Lcb_31495_1:
	s_or_b64 exec, exec, s[54:55]
	v_cmp_gt_i32_e32 vcc, s76, v123
	v_mov_b32_e32 v44, 0
	v_mov_b32_e32 v45, 0
	v_mov_b32_e32 v46, 0
	v_mov_b32_e32 v47, 0
	v_mov_b32_e32 v48, 0
	v_mov_b32_e32 v49, 0
	v_mov_b32_e32 v50, 0
	v_mov_b32_e32 v51, 0
	s_and_saveexec_b64 s[54:55], vcc
	s_cbranch_execz .Lcb_31495_2
	v_add_u32_e32 v2, s77, v123
	v_ashrrev_i32_e32 v3, 31, v2
	v_lshlrev_b64 v[2:3], 10, v[2:3]
	v_lshl_or_b32 v2, v150, 1, v2
	v_lshl_add_u64 v[48:49], s[80:81], 0, v[2:3]
	v_lshl_add_u64 v[2:3], s[88:89], 0, v[2:3]
	global_load_dwordx4 v[44:47], v[48:49], off
	s_nop 0
	global_load_dwordx4 v[48:51], v[2:3], off
.Lcb_31495_2:
	s_or_b64 exec, exec, s[54:55]
	v_cmp_gt_i32_e32 vcc, s76, v125
	v_mov_b32_e32 v52, 0
	v_mov_b32_e32 v53, 0
	v_mov_b32_e32 v54, 0
	v_mov_b32_e32 v55, 0
	v_mov_b32_e32 v56, 0
	v_mov_b32_e32 v57, 0
	v_mov_b32_e32 v58, 0
	v_mov_b32_e32 v59, 0
	s_and_saveexec_b64 s[54:55], vcc
	s_cbranch_execz .Lcb_31495_3
	v_add_u32_e32 v2, s77, v125
	v_ashrrev_i32_e32 v3, 31, v2
	v_lshlrev_b64 v[2:3], 10, v[2:3]
	v_lshl_or_b32 v2, v150, 1, v2
	v_lshl_add_u64 v[56:57], s[80:81], 0, v[2:3]
	v_lshl_add_u64 v[2:3], s[88:89], 0, v[2:3]
	global_load_dwordx4 v[52:55], v[56:57], off
	s_nop 0
	global_load_dwordx4 v[56:59], v[2:3], off
.Lcb_31495_3:
	s_or_b64 exec, exec, s[54:55]
	s_waitcnt vmcnt(0)
	ds_write_b128 v120, v[66:69]
	ds_write_b128 v120, v[62:65] offset:62464
	ds_write_b128 v122, v[36:39]
	ds_write_b128 v122, v[40:43] offset:62464
	ds_write_b128 v124, v[44:47]
	ds_write_b128 v124, v[48:51] offset:62464
	ds_write_b128 v126, v[52:55]
	ds_write_b128 v126, v[56:59] offset:62464
	s_add_i32 s82, s82, 1
	s_cmp_ge_u32 s82, s68
	s_waitcnt lgkmcnt(0)
	s_barrier
	s_cbranch_scc1 .LBB0_1708
	s_add_i32 s2, s74, 1
	s_cmpk_lt_i32 s74, 0xff
	s_cselect_b64 s[54:55], -1, 0
	s_and_b64 s[56:57], s[54:55], exec
	s_mul_i32 s90, s2, 0xc00
	v_mov_b32_e32 v40, v0
	v_mov_b32_e32 v41, v0
	s_cselect_b32 s74, 64, 16
	s_mul_hi_i32 s75, s2, 0xc00
	s_add_u32 s56, s90, s1
	v_mov_b32_e32 v42, v0
	v_mov_b32_e32 v43, v0
	v_mov_b64_e32 v[36:37], v[40:41]
	v_cmp_gt_u32_e32 vcc, s74, v107
	s_addc_u32 s57, s75, 0
	v_mov_b64_e32 v[38:39], v[42:43]
	s_and_saveexec_b64 s[58:59], vcc
	s_cbranch_execz .LBB0_1695
	v_lshl_add_u64 v[2:3], s[56:57], 0, v[112:113]
	v_lshlrev_b64 v[2:3], 7, v[2:3]
	v_lshl_add_u64 v[2:3], v[100:101], 0, v[2:3]
	global_load_dwordx4 v[36:39], v[2:3], off

.Lqk_43407_0:
	s_or_b64 exec, exec, s[42:43]
	v_cmp_gt_i32_e32 vcc, s60, v153
	v_mov_b32_e32 v36, 0
	v_mov_b32_e32 v37, 0
	v_mov_b32_e32 v38, 0
	v_mov_b32_e32 v39, 0
	v_mov_b32_e32 v40, 0
	v_mov_b32_e32 v41, 0
	v_mov_b32_e32 v42, 0
	v_mov_b32_e32 v43, 0
	s_and_saveexec_b64 s[42:43], vcc
	s_cbranch_execz .Lqk_43407_1
	v_add_u32_e32 v2, s59, v153
	v_ashrrev_i32_e32 v3, 31, v2
	v_lshlrev_b64 v[2:3], 10, v[2:3]
	v_lshl_or_b32 v2, v172, 1, v2
	v_lshl_add_u64 v[40:41], s[96:97], 0, v[2:3]
	v_lshl_add_u64 v[2:3], s[94:95], 0, v[2:3]
	global_load_dwordx4 v[36:39], v[2:3], off
	s_nop 0
	global_load_dwordx4 v[40:43], v[40:41], off
.Lqk_43407_1:
	s_or_b64 exec, exec, s[42:43]
	v_cmp_gt_i32_e32 vcc, s60, v155
	v_mov_b32_e32 v44, 0
	v_mov_b32_e32 v45, 0
	v_mov_b32_e32 v46, 0
	v_mov_b32_e32 v47, 0
	v_mov_b32_e32 v48, 0
	v_mov_b32_e32 v49, 0
	v_mov_b32_e32 v50, 0
	v_mov_b32_e32 v51, 0
	s_and_saveexec_b64 s[42:43], vcc
	s_cbranch_execz .Lqk_43407_2
	v_add_u32_e32 v2, s59, v155
	v_ashrrev_i32_e32 v3, 31, v2
	v_lshlrev_b64 v[2:3], 10, v[2:3]
	v_lshl_or_b32 v2, v172, 1, v2
	v_lshl_add_u64 v[48:49], s[96:97], 0, v[2:3]
	v_lshl_add_u64 v[2:3], s[94:95], 0, v[2:3]
	global_load_dwordx4 v[44:47], v[2:3], off
	s_nop 0
	global_load_dwordx4 v[48:51], v[48:49], off
.Lqk_43407_2:
	s_or_b64 exec, exec, s[42:43]
	v_cmp_gt_i32_e32 vcc, s60, v157
	v_mov_b32_e32 v52, 0
	v_mov_b32_e32 v53, 0
	v_mov_b32_e32 v54, 0
	v_mov_b32_e32 v55, 0
	v_mov_b32_e32 v64, 0
	v_mov_b32_e32 v65, 0
	v_mov_b32_e32 v66, 0
	v_mov_b32_e32 v67, 0
	s_and_saveexec_b64 s[42:43], vcc
	s_cbranch_execz .Lqk_43407_3
	v_add_u32_e32 v2, s59, v157
	v_ashrrev_i32_e32 v3, 31, v2
	v_lshlrev_b64 v[2:3], 10, v[2:3]
	v_lshl_or_b32 v2, v172, 1, v2
	v_lshl_add_u64 v[64:65], s[96:97], 0, v[2:3]
	v_lshl_add_u64 v[2:3], s[94:95], 0, v[2:3]
	global_load_dwordx4 v[52:55], v[2:3], off
	s_nop 0
	global_load_dwordx4 v[64:67], v[64:65], off
.Lqk_43407_3:
	s_or_b64 exec, exec, s[42:43]
	s_waitcnt vmcnt(0)
	ds_write_b128 v152, v[74:77] offset:27648
	ds_write_b128 v152, v[70:73] offset:45056
	ds_write_b128 v154, v[36:39] offset:27648
	ds_write_b128 v154, v[40:43] offset:45056
	ds_write_b128 v156, v[44:47] offset:27648
	ds_write_b128 v156, v[48:51] offset:45056
	ds_write_b128 v158, v[52:55] offset:27648
	ds_write_b128 v158, v[64:67] offset:45056
	s_add_i32 s58, s58, 1
	s_cmp_ge_u32 s58, s3
	v_mov_b64_e32 v[70:71], v[62:63]
	v_mov_b64_e32 v[68:69], v[60:61]
	v_mov_b64_e32 v[74:75], v[58:59]
	v_mov_b64_e32 v[72:73], v[56:57]
	s_waitcnt lgkmcnt(0)
	s_barrier
	s_cbranch_scc1 .LBB0_2424
	s_add_i32 s42, s44, 1
	s_cmpk_lt_i32 s44, 0xff
	s_cselect_b64 s[44:45], -1, 0
	s_ashr_i32 s43, s42, 31
	v_mov_b32_e32 v40, v0
	v_mov_b32_e32 v41, v0
	s_lshl_b64 s[46:47], s[42:43], 9
	v_mov_b32_e32 v42, v0
	v_mov_b32_e32 v43, v0
	v_mov_b64_e32 v[36:37], v[40:41]
	s_or_b64 s[44:45], s[44:45], s[6:7]
	s_or_b64 s[46:47], s[46:47], s[0:1]
	v_mov_b64_e32 v[38:39], v[42:43]
	s_and_saveexec_b64 s[52:53], s[44:45]
	s_cbranch_execz .LBB0_2413
	v_lshl_add_u64 v[2:3], s[46:47], 0, v[144:145]
	v_lshlrev_b64 v[2:3], 7, v[2:3]
	v_lshl_add_u64 v[2:3], v[130:131], 0, v[2:3]
	global_load_dwordx4 v[36:39], v[2:3], off
